# phase C: the trailing key-norm item's eight row loads prefetched into registers during the last S5 item (next-item prefetch extended)
# baseline (speedup 1.0000x reference)
; DI void phaseC(int wv0, PP p, unsigned char* smem) {
;     ...
;       const u16* K = (const u16*)(p->ws + (tns ? OFF_KW : OFF_KS)) + ((size_t)bg * S_ + part * 512 + tid) * 64;
;       float q2 = 0.f;
; #pragma unroll
;       for (int c = 0; c < 8; ++c) {
;         const uint4 w = *(const uint4*)(K + c * 8);
.Lmy_cpf2_use:
	s_waitcnt vmcnt(0)
	v_mov_b32_e32 v2, v210
	v_mov_b32_e32 v3, v211
	v_mov_b32_e32 v4, v212
	v_mov_b32_e32 v5, v213
	v_mov_b32_e32 v6, v214
	v_mov_b32_e32 v7, v215
	v_mov_b32_e32 v8, v216
	v_mov_b32_e32 v9, v217
	v_mov_b32_e32 v10, v218
	v_mov_b32_e32 v11, v219
	v_mov_b32_e32 v12, v220
	v_mov_b32_e32 v13, v221
	v_mov_b32_e32 v14, v222
	v_mov_b32_e32 v15, v223
	v_mov_b32_e32 v16, v224
	v_mov_b32_e32 v17, v225
	v_mov_b32_e32 v18, v226
	v_mov_b32_e32 v19, v227
	v_mov_b32_e32 v20, v228
	v_mov_b32_e32 v21, v229
	v_mov_b32_e32 v22, v230
	v_mov_b32_e32 v23, v231
	v_mov_b32_e32 v24, v232
	v_mov_b32_e32 v25, v233
	v_mov_b32_e32 v26, v234
	v_mov_b32_e32 v27, v235
	v_mov_b32_e32 v28, v236
	v_mov_b32_e32 v29, v237
	v_mov_b32_e32 v30, v238
	v_mov_b32_e32 v31, v239
	v_mov_b32_e32 v32, v240
	v_mov_b32_e32 v33, v241
	s_branch .Lmy_cpf2_join

; template <bool OUT>
; DI void s5_item(int wv0, PP p, int item, unsigned char* smem) {
;     ...
;   *(uint4*)(smem + tid * 16) = *(const uint4*)(p->ws + OFF_S5T + (size_t)g * 8192 + tid * 16);
;   const float2 lb = ((const float2*)(p->ws + OFF_S5L))[g * 64 + lane];
;   const float lbr = lb.x, lbi = lb.y;
;   float2* HL = (float2*)(p->ws + OFF_HLOC) + ((size_t)(b * 128 + ch) * 32 + g) * 64 + lane;
;   float hr = 0.f, hi = 0.f;
;   if (OUT) { const float2 h0 = *HL; hr = h0.x; hi = h0.y; }
;   const u16* U = (const u16*)(p->ws + OFF_U) + ((size_t)(b * S_ + ch * 64)) * 512 + g * 16;
;   u16* YS = (u16*)(p->ws + OFF_YS) + ((size_t)(b * S_ + ch * 64)) * 512 + g * 16;
;   const float dk = p->dsk[g * 16 + fr];
;   const bf16x8 zero8 = {0, 0, 0, 0, 0, 0, 0, 0};
;   bf16x8 uall[4];
;   u16 usk[4][4];
; #pragma unroll
;   for (int sub = 0; sub < 4; ++sub) {
;     uall[sub] = fq < 2 ? *(const bf16x8*)(U + (size_t)(sub * 16 + fr) * 512 + 8 * fq) : zero8;
;     if (OUT) {
; #pragma unroll
;       for (int j = 0; j < 4; ++j) usk[sub][j] = U[(size_t)(sub * 16 + 4 * fq + j) * 512 + fr];
;     }
;   }
; DI void phaseC(int wv0, PP p, unsigned char* smem) {
;   for (int id = blockIdx.x; id < 128 + 2048 + 256; id += gridDim.x) {
;     if (id >= 128 + 2048) {
;       const int it = id - (128 + 2048), tns = it >> 7, bg = (it >> 4) & 7, part = it & 15;
;       const int tid = my_tid(wv0);
;       const u16* K = (const u16*)(p->ws + (tns ? OFF_KW : OFF_KS)) + ((size_t)bg * S_ + part * 512 + tid) * 64;
;       float q2 = 0.f;
; #pragma unroll
;       for (int c = 0; c < 8; ++c) {
;         const uint4 w = *(const uint4*)(K + c * 8);
.LBB0_424:
	s_or_b64 exec, exec, s[44:45]
	v_lshl_add_u32 v5, v53, 5, 32
	v_mov_b32_e32 v4, 0
	v_add_u32_e32 v54, v5, v128
	v_mov_b32_e32 v8, 0
	v_mov_b32_e32 v9, 0
	v_mov_b32_e32 v10, 0
	v_mov_b32_e32 v11, 0
	s_waitcnt vmcnt(4)
	ds_write_b128 v204, v[200:203]
	s_waitcnt lgkmcnt(0)
	s_barrier
	s_and_saveexec_b64 s[44:45], s[2:3]
	ds_read_b128 v[8:11], v54
	s_or_b64 exec, exec, s[44:45]
	v_mov_b32_e32 v5, 0
	v_mov_b32_e32 v6, 0
	v_mov_b32_e32 v7, 0
	s_and_saveexec_b64 s[44:45], s[2:3]
	ds_read_b128 v[4:7], v54 offset:512
	s_or_b64 exec, exec, s[44:45]
	v_mov_b32_e32 v16, 0
	v_mov_b32_e32 v20, 0
	v_mov_b32_e32 v21, 0
	v_mov_b32_e32 v22, 0
	v_mov_b32_e32 v23, 0
	s_and_saveexec_b64 s[44:45], s[2:3]
	ds_read_b128 v[20:23], v54 offset:1024
	s_or_b64 exec, exec, s[44:45]
	v_mov_b32_e32 v17, 0
	v_mov_b32_e32 v18, 0
	v_mov_b32_e32 v19, 0
	s_and_saveexec_b64 s[44:45], s[2:3]
	ds_read_b128 v[16:19], v54 offset:1536
	s_or_b64 exec, exec, s[44:45]
	v_mov_b32_e32 v24, 0
	v_mov_b32_e32 v32, 0
	v_mov_b32_e32 v33, 0
	v_mov_b32_e32 v34, 0
	v_mov_b32_e32 v35, 0
	s_and_saveexec_b64 s[44:45], s[2:3]
	ds_read_b128 v[32:35], v54 offset:2048
	s_or_b64 exec, exec, s[44:45]
	v_mov_b32_e32 v25, 0
	v_mov_b32_e32 v26, 0
	v_mov_b32_e32 v27, 0
	s_and_saveexec_b64 s[44:45], s[2:3]
	ds_read_b128 v[24:27], v54 offset:2560
	s_or_b64 exec, exec, s[44:45]
	v_mov_b32_e32 v36, 0
	v_mov_b32_e32 v40, 0
	v_mov_b32_e32 v41, 0
	v_mov_b32_e32 v42, 0
	v_mov_b32_e32 v43, 0
	s_and_saveexec_b64 s[44:45], s[2:3]
	ds_read_b128 v[40:43], v54 offset:3072
	s_or_b64 exec, exec, s[44:45]
	s_mov_b32 s14, 0
	v_mov_b32_e32 v37, 0
	v_mov_b32_e32 v38, 0
	v_mov_b32_e32 v39, 0
	s_and_saveexec_b64 s[44:45], s[2:3]
	ds_read_b128 v[36:39], v54 offset:3584
	s_or_b64 exec, exec, s[44:45]
	s_waitcnt vmcnt(0) lgkmcnt(0)
	s_load_dword s79, s[12:13], 0x0
	s_load_dwordx2 s[80:81], s[6:7], 0xc8
	s_mov_b32 s78, -1
	s_waitcnt lgkmcnt(0)
	s_add_i32 s79, s79, s64
	s_cmpk_lt_i32 s79, 0x880
	s_cbranch_scc0 .Lmy_cpf2
	s_mov_b32 s78, s79
	s_add_i32 s83, s79, 0xffffff80
	s_lshr_b32 s84, s83, 9
	s_bfe_u32 s85, s83, 0x50004
	s_lshl_b32 s83, s83, 3
	s_and_b32 s83, s83, 0x78
	s_add_i32 s83, s83, s89
	s_lshl_b32 s86, s85, 13
	s_add_u32 s86, s80, s86
	s_addc_u32 s87, s81, 0
	v_lshlrev_b32_e32 v232, 4, v144
	v_ashrrev_i32_e32 v233, 31, v232
	v_lshl_add_u64 v[234:235], s[86:87], 0, v[232:233]
	v_add_co_u32_e32 v234, vcc, s59, v234
	s_nop 1
	v_addc_co_u32_e32 v235, vcc, 0, v235, vcc
	global_load_dwordx4 v[210:213], v[234:235], off offset:256
	v_and_b32_e32 v236, 63, v144
	v_lshlrev_b32_e32 v237, 3, v236
	v_lshl_or_b32 v238, s85, 9, v237
	v_mov_b32_e32 v239, 0
	v_lshl_add_u64 v[240:241], s[80:81], 0, v[238:239]
	v_add_co_u32_e32 v240, vcc, s60, v240
	s_nop 1
	v_addc_co_u32_e32 v241, vcc, 0, v241, vcc
	global_load_dwordx2 v[214:215], v[240:241], off offset:256
	s_lshl_b32 s86, s84, 13
	s_lshl_b32 s87, s83, 6
	s_add_i32 s86, s87, s86
	s_mov_b32 s87, 0
	s_lshl_b64 s[86:87], s[86:87], 10
	s_add_u32 s86, s80, s86
	s_addc_u32 s87, s81, s87
	s_lshl_b32 s88, s85, 5
	s_add_u32 s86, s86, s88
	s_addc_u32 s87, s87, 0
	v_and_b32_e32 v238, 48, v144
	v_lshl_add_u64 v[240:241], s[86:87], 0, v[238:239]
	v_lshl_add_u64 v[240:241], v[240:241], 0, s[16:17]
	v_and_b32_e32 v242, 15, v144
	v_lshlrev_b32_e32 v242, 10, v242
	v_mov_b32_e32 v243, 0
	v_lshl_add_u64 v[240:241], v[240:241], 0, v[242:243]
	v_cmp_gt_u32_e64 s[86:87], 32, v236
	s_and_saveexec_b64 s[86:87], s[86:87]
	global_load_dwordx4 v[216:219], v[240:241], off
	v_add_co_u32_e32 v244, vcc, 0x4000, v240
	s_nop 1
	v_addc_co_u32_e32 v245, vcc, 0, v241, vcc
	global_load_dwordx4 v[220:223], v[244:245], off
	v_add_co_u32_e32 v244, vcc, 0x8000, v240
	s_nop 1
	v_addc_co_u32_e32 v245, vcc, 0, v241, vcc
	global_load_dwordx4 v[224:227], v[244:245], off
	v_add_co_u32_e32 v244, vcc, 0xc000, v240
	s_nop 1
	v_addc_co_u32_e32 v245, vcc, 0, v241, vcc
	global_load_dwordx4 v[228:231], v[244:245], off
	s_or_b64 exec, exec, s[86:87]
	s_branch .Lmy_cpf_none
.Lmy_cpf2:
	s_cmpk_lt_i32 s79, 0x980
	s_cbranch_scc0 .Lmy_cpf_none
	s_mov_b32 s78, s79
	s_add_i32 s83, s79, 0xfffff780
	s_bfe_u32 s84, s79, 0x30004
	s_cmpk_lt_u32 s83, 0x80
	s_cselect_b32 s85, s63, 0x153d4100
	s_add_u32 s86, s80, s85
	s_addc_u32 s87, s81, 0
	s_lshl_b32 s85, s79, 9
	s_lshl_b32 s84, s84, 13
	s_and_b32 s85, s85, 0x1e00
	s_or_b32 s84, s84, s85
	s_mov_b32 s85, 0
	v_mov_b32_e32 v242, v144
	v_ashrrev_i32_e32 v243, 31, v144
	v_lshl_add_u64 v[242:243], s[84:85], 0, v[242:243]
	v_lshlrev_b64 v[242:243], 7, v[242:243]
	v_lshl_add_u64 v[242:243], s[86:87], 0, v[242:243]
	global_load_dwordx4 v[210:213], v[242:243], off
	global_load_dwordx4 v[214:217], v[242:243], off offset:16
	global_load_dwordx4 v[218:221], v[242:243], off offset:32
	global_load_dwordx4 v[222:225], v[242:243], off offset:48
	global_load_dwordx4 v[226:229], v[242:243], off offset:64
	global_load_dwordx4 v[230:233], v[242:243], off offset:80
	global_load_dwordx4 v[234:237], v[242:243], off offset:112
	global_load_dwordx4 v[238:241], v[242:243], off offset:96

; DI void phaseC(int wv0, PP p, unsigned char* smem) {
;     ...
;       const int it = id - (128 + 2048), tns = it >> 7, bg = (it >> 4) & 7, part = it & 15;
;       const int tid = my_tid(wv0);
;       const u16* K = (const u16*)(p->ws + (tns ? OFF_KW : OFF_KS)) + ((size_t)bg * S_ + part * 512 + tid) * 64;
;       float q2 = 0.f;
; #pragma unroll
;       for (int c = 0; c < 8; ++c) {
;         const uint4 w = *(const uint4*)(K + c * 8);
.LBB0_459:
	v_mov_b32_e32 v0, v144
	s_load_dwordx2 s[2:3], s[6:7], 0xc8
	s_add_i32 s66, s64, 0xfffff780
	s_bfe_u32 s65, s64, 0x30004
	s_cmpk_lt_u32 s66, 0x80
	s_cselect_b32 s14, s63, 0x153d4100
	s_waitcnt lgkmcnt(0)
	s_add_u32 s42, s2, s14
	s_addc_u32 s43, s3, 0
	s_lshl_b32 s44, s64, 9
	s_lshl_b32 s14, s65, 13
	s_and_b32 s44, s44, 0x1e00
	s_or_b32 s14, s14, s44
	v_ashrrev_i32_e32 v1, 31, v0
	v_lshl_add_u64 v[2:3], s[14:15], 0, v[0:1]
	v_lshlrev_b64 v[2:3], 7, v[2:3]
	v_lshl_add_u64 v[30:31], s[42:43], 0, v[2:3]
	s_cmp_eq_u32 s78, s64
	s_cbranch_scc1 .Lmy_cpf2_use
	global_load_dwordx4 v[2:5], v[30:31], off
	global_load_dwordx4 v[6:9], v[30:31], off offset:16
	global_load_dwordx4 v[10:13], v[30:31], off offset:32
	global_load_dwordx4 v[14:17], v[30:31], off offset:48
	global_load_dwordx4 v[18:21], v[30:31], off offset:64
	global_load_dwordx4 v[22:25], v[30:31], off offset:80
	global_load_dwordx4 v[26:29], v[30:31], off offset:112
	s_nop 0
	global_load_dwordx4 v[30:33], v[30:31], off offset:96
; DI void phaseC(int wv0, PP p, unsigned char* smem) {
;     ...
;       float q2 = 0.f;
; #pragma unroll
;       for (int c = 0; c < 8; ++c) {
;         const uint4 w = *(const uint4*)(K + c * 8);
;         const unsigned ww[4] = {w.x, w.y, w.z, w.w};
; #pragma unroll
;         for (int e = 0; e < 4; ++e) {
;           const float a = __uint_as_float(ww[e] << 16), b2 = __uint_as_float(ww[e] & 0xffff0000u);
;           q2 += a * a + b2 * b2;
;         }
;       }
; #pragma unroll
;       for (int o = 32; o > 0; o >>= 1) q2 = fmaxf(q2, __shfl_xor(q2, o));
;       if ((tid & 63) == 0) atomicMax((unsigned*)(p->ws + OFF_KMAX) + tns * 8 + bg, __float_as_uint(q2));
.Lmy_cpf2_join:
	v_and_b32_e32 v0, 63, v0
	s_waitcnt vmcnt(0)
	v_lshlrev_b32_e32 v1, 16, v2
	v_and_b32_e32 v2, 0xffff0000, v2
	v_lshlrev_b32_e32 v34, 16, v3
	v_and_b32_e32 v3, 0xffff0000, v3
	v_lshlrev_b32_e32 v35, 16, v4
	v_and_b32_e32 v4, 0xffff0000, v4
	v_mul_f32_e32 v2, v2, v2
	v_mul_f32_e32 v3, v3, v3
	v_lshlrev_b32_e32 v36, 16, v5
	v_and_b32_e32 v5, 0xffff0000, v5
	v_mul_f32_e32 v4, v4, v4
	v_fmac_f32_e32 v2, v1, v1
	v_fmac_f32_e32 v3, v34, v34
	v_lshlrev_b32_e32 v37, 16, v6
	v_and_b32_e32 v6, 0xffff0000, v6
	v_mul_f32_e32 v5, v5, v5
	v_fmac_f32_e32 v4, v35, v35
	v_add_f32_e32 v1, v2, v3
	v_lshlrev_b32_e32 v38, 16, v7
	v_and_b32_e32 v7, 0xffff0000, v7
	v_mul_f32_e32 v6, v6, v6
	v_fmac_f32_e32 v5, v36, v36
	v_add_f32_e32 v1, v1, v4
	v_lshlrev_b32_e32 v39, 16, v8
	v_and_b32_e32 v8, 0xffff0000, v8
	v_mul_f32_e32 v7, v7, v7
	v_fmac_f32_e32 v6, v37, v37
	v_add_f32_e32 v1, v1, v5
	v_lshlrev_b32_e32 v40, 16, v9
	v_and_b32_e32 v9, 0xffff0000, v9
	v_mul_f32_e32 v8, v8, v8
	v_fmac_f32_e32 v7, v38, v38
	v_add_f32_e32 v1, v1, v6
	v_lshlrev_b32_e32 v41, 16, v10
	v_and_b32_e32 v10, 0xffff0000, v10
	v_mul_f32_e32 v9, v9, v9
	v_fmac_f32_e32 v8, v39, v39
	v_add_f32_e32 v1, v1, v7
	v_lshlrev_b32_e32 v42, 16, v11
	v_and_b32_e32 v11, 0xffff0000, v11
	v_mul_f32_e32 v10, v10, v10
	v_fmac_f32_e32 v9, v40, v40
	v_add_f32_e32 v1, v1, v8
	v_lshlrev_b32_e32 v43, 16, v12
	v_and_b32_e32 v12, 0xffff0000, v12
	v_mul_f32_e32 v11, v11, v11
	v_fmac_f32_e32 v10, v41, v41
	v_add_f32_e32 v1, v1, v9
	v_lshlrev_b32_e32 v44, 16, v13
	v_and_b32_e32 v13, 0xffff0000, v13
	v_mul_f32_e32 v12, v12, v12
	v_fmac_f32_e32 v11, v42, v42
	v_add_f32_e32 v1, v1, v10
	v_lshlrev_b32_e32 v45, 16, v14
	v_and_b32_e32 v14, 0xffff0000, v14
	v_mul_f32_e32 v13, v13, v13
	v_fmac_f32_e32 v12, v43, v43
	v_add_f32_e32 v1, v1, v11
	v_lshlrev_b32_e32 v46, 16, v15
	v_and_b32_e32 v15, 0xffff0000, v15
	v_mul_f32_e32 v14, v14, v14
	v_fmac_f32_e32 v13, v44, v44
	v_add_f32_e32 v1, v1, v12
	v_lshlrev_b32_e32 v47, 16, v16
	v_and_b32_e32 v16, 0xffff0000, v16
	v_mul_f32_e32 v15, v15, v15
	v_fmac_f32_e32 v14, v45, v45
	v_add_f32_e32 v1, v1, v13
	v_lshlrev_b32_e32 v48, 16, v17
	v_and_b32_e32 v17, 0xffff0000, v17
	v_mul_f32_e32 v16, v16, v16
	v_fmac_f32_e32 v15, v46, v46
	v_add_f32_e32 v1, v1, v14
	v_lshlrev_b32_e32 v49, 16, v18
	v_and_b32_e32 v18, 0xffff0000, v18
	v_mul_f32_e32 v17, v17, v17
	v_fmac_f32_e32 v16, v47, v47
	v_add_f32_e32 v1, v1, v15
	v_lshlrev_b32_e32 v50, 16, v19
	v_and_b32_e32 v19, 0xffff0000, v19
	v_mul_f32_e32 v18, v18, v18
	v_fmac_f32_e32 v17, v48, v48
	v_add_f32_e32 v1, v1, v16
	v_mul_f32_e32 v19, v19, v19
	v_fmac_f32_e32 v18, v49, v49
	v_add_f32_e32 v1, v1, v17
	v_and_b32_e32 v3, 0xffff0000, v20
	v_add_f32_e32 v1, v1, v18
	v_fmac_f32_e32 v19, v50, v50
	v_lshlrev_b32_e32 v2, 16, v20
	v_mul_f32_e32 v3, v3, v3
	v_add_f32_e32 v1, v1, v19
	v_fmac_f32_e32 v3, v2, v2
	v_add_f32_e32 v1, v1, v3
	v_and_b32_e32 v3, 0xffff0000, v21
	v_lshlrev_b32_e32 v2, 16, v21
	v_mul_f32_e32 v3, v3, v3
	v_fmac_f32_e32 v3, v2, v2
	v_add_f32_e32 v1, v1, v3
	v_and_b32_e32 v3, 0xffff0000, v22
	v_lshlrev_b32_e32 v2, 16, v22
	v_mul_f32_e32 v3, v3, v3
	v_fmac_f32_e32 v3, v2, v2
	v_add_f32_e32 v1, v1, v3
	v_and_b32_e32 v3, 0xffff0000, v23
	v_lshlrev_b32_e32 v2, 16, v23
	v_mul_f32_e32 v3, v3, v3
	v_fmac_f32_e32 v3, v2, v2
	v_add_f32_e32 v1, v1, v3
	v_and_b32_e32 v3, 0xffff0000, v24
	v_lshlrev_b32_e32 v2, 16, v24
	v_mul_f32_e32 v3, v3, v3
	v_fmac_f32_e32 v3, v2, v2
	v_add_f32_e32 v1, v1, v3
	v_and_b32_e32 v3, 0xffff0000, v25
	v_lshlrev_b32_e32 v2, 16, v25
	v_mul_f32_e32 v3, v3, v3
	v_fmac_f32_e32 v3, v2, v2
	v_add_f32_e32 v1, v1, v3
	v_and_b32_e32 v3, 0xffff0000, v30
	v_lshlrev_b32_e32 v2, 16, v30
	v_mul_f32_e32 v3, v3, v3
	v_fmac_f32_e32 v3, v2, v2
	v_add_f32_e32 v1, v1, v3
	v_and_b32_e32 v3, 0xffff0000, v31
	v_lshlrev_b32_e32 v2, 16, v31
	v_mul_f32_e32 v3, v3, v3
	v_fmac_f32_e32 v3, v2, v2
	v_add_f32_e32 v1, v1, v3
	v_and_b32_e32 v3, 0xffff0000, v32
	v_lshlrev_b32_e32 v2, 16, v32
	v_mul_f32_e32 v3, v3, v3
	v_fmac_f32_e32 v3, v2, v2
	v_add_f32_e32 v1, v1, v3
	v_and_b32_e32 v3, 0xffff0000, v33
	v_lshlrev_b32_e32 v2, 16, v33
	v_mul_f32_e32 v3, v3, v3
	v_fmac_f32_e32 v3, v2, v2
	v_add_f32_e32 v1, v1, v3
	v_and_b32_e32 v3, 0xffff0000, v26
	v_lshlrev_b32_e32 v2, 16, v26
	v_mul_f32_e32 v3, v3, v3
	v_fmac_f32_e32 v3, v2, v2
	v_add_f32_e32 v1, v1, v3
	v_and_b32_e32 v3, 0xffff0000, v27
	v_lshlrev_b32_e32 v2, 16, v27
	v_mul_f32_e32 v3, v3, v3
	v_fmac_f32_e32 v3, v2, v2
	v_add_f32_e32 v1, v1, v3
	v_and_b32_e32 v3, 0xffff0000, v28
	v_lshlrev_b32_e32 v2, 16, v28
	v_mul_f32_e32 v3, v3, v3
	v_fmac_f32_e32 v3, v2, v2
	v_add_f32_e32 v1, v1, v3
	v_and_b32_e32 v3, 0xffff0000, v29
	v_lshlrev_b32_e32 v2, 16, v29
	v_mul_f32_e32 v3, v3, v3
	v_fmac_f32_e32 v3, v2, v2
	v_and_b32_e32 v2, 64, v143
	v_add_f32_e32 v1, v1, v3
	v_add_u32_e32 v2, 64, v2
	v_xor_b32_e32 v3, 32, v143
	v_cmp_lt_i32_e32 vcc, v3, v2
	s_nop 1
	v_cndmask_b32_e32 v3, v143, v3, vcc
	v_lshlrev_b32_e32 v3, 2, v3
	ds_bpermute_b32 v3, v3, v1
	s_waitcnt lgkmcnt(0)
	v_max_f32_e32 v3, v3, v3
	v_max_f32_e32 v1, v1, v3
	v_xor_b32_e32 v3, 16, v143
	v_cmp_lt_i32_e32 vcc, v3, v2
	s_nop 1
	v_cndmask_b32_e32 v3, v143, v3, vcc
	v_lshlrev_b32_e32 v3, 2, v3
	ds_bpermute_b32 v3, v3, v1
	s_waitcnt lgkmcnt(0)
	v_max_f32_e32 v3, v3, v3
	v_max_f32_e32 v1, v1, v3
	v_xor_b32_e32 v3, 8, v143
	v_cmp_lt_i32_e32 vcc, v3, v2
	s_nop 1
	v_cndmask_b32_e32 v3, v143, v3, vcc
	v_lshlrev_b32_e32 v3, 2, v3
	ds_bpermute_b32 v3, v3, v1
	s_waitcnt lgkmcnt(0)
	v_max_f32_e32 v3, v3, v3
	v_max_f32_e32 v1, v1, v3
	v_xor_b32_e32 v3, 4, v143
	v_cmp_lt_i32_e32 vcc, v3, v2
	s_nop 1
	v_cndmask_b32_e32 v3, v143, v3, vcc
	v_lshlrev_b32_e32 v3, 2, v3
	ds_bpermute_b32 v3, v3, v1
	s_waitcnt lgkmcnt(0)
	v_max_f32_e32 v3, v3, v3
	v_max_f32_e32 v1, v1, v3
	v_xor_b32_e32 v3, 2, v143
	v_cmp_lt_i32_e32 vcc, v3, v2
	s_nop 1
	v_cndmask_b32_e32 v3, v143, v3, vcc
	v_lshlrev_b32_e32 v3, 2, v3
	ds_bpermute_b32 v3, v3, v1
	s_waitcnt lgkmcnt(0)
	v_max_f32_e32 v3, v3, v3
	v_max_f32_e32 v1, v1, v3
	v_xor_b32_e32 v3, 1, v143
	v_cmp_lt_i32_e32 vcc, v3, v2
	s_nop 1
	v_cndmask_b32_e32 v2, v143, v3, vcc
	v_lshlrev_b32_e32 v2, 2, v2
	ds_bpermute_b32 v2, v2, v1
	v_cmp_eq_u32_e32 vcc, 0, v0
	s_and_saveexec_b64 s[42:43], vcc
	s_cbranch_execz .LBB0_412
	s_waitcnt lgkmcnt(0)
	v_max_f32_e32 v0, v2, v2
	v_max_f32_e32 v1, v1, v1
	s_mov_b64 s[44:45], exec
	v_max_f32_e32 v0, v1, v0
	s_mov_b32 s14, 0
